# combine phase: end-of-row wait counted (vmcnt(3)) so the row's own stores are not waited for
# baseline (speedup 1.0000x reference)
.LBB0_55:
	v_mov_b64_e32 v[80:81], v[188:189]
	v_mov_b64_e32 v[82:83], v[190:191]
	v_mov_b64_e32 v[90:91], v[210:211]
	v_mov_b64_e32 v[92:93], v[212:213]
	v_mov_b64_e32 v[94:95], v[226:227]
	v_mov_b64_e32 v[96:97], v[228:229]
	v_mov_b32_e32 v23, v30
	v_lshlrev_b32_e32 v30, 16, v34
	v_and_b32_e32 v31, 0xffff0000, v34
	v_mov_b32_e32 v25, v32
	v_mov_b32_e32 v32, v86
	v_mov_b32_e32 v33, v86
	v_lshlrev_b32_e32 v34, 16, v35
	v_and_b32_e32 v35, 0xffff0000, v35
	v_pk_mul_f32 v[26:27], v[26:27], v[30:31]
	v_pk_mul_f32 v[22:23], v[22:23], v[32:33]
	v_pk_mul_f32 v[24:25], v[24:25], v[86:87]
	v_pk_mul_f32 v[28:29], v[28:29], v[34:35]
	v_pk_mul_f32 v[26:27], v[26:27], v[84:85]
	v_mov_b32_e32 v85, v84
	v_pk_mul_f32 v[28:29], v[28:29], v[84:85]
	s_and_b64 vcc, exec, s[14:15]
	s_mov_b64 s[14:15], -1
	v_pk_fma_f32 v[22:23], v[22:23], v[82:83], v[92:93]
	v_pk_fma_f32 v[30:31], v[24:25], v[80:81], v[90:91]
	s_waitcnt vmcnt(3)
	v_pk_fma_f32 v[24:25], v[28:29], v[96:97], v[22:23]
	v_pk_fma_f32 v[22:23], v[26:27], v[94:95], v[30:31]
	global_store_dwordx4 v[18:19], v[22:25], off offset:3072 nt
	v_cvt_pk_bf16_f32 v18, v22, v23
	v_cvt_pk_bf16_f32 v19, v24, v25
	s_cbranch_vccnz .LBB0_59
	s_and_b64 vcc, exec, s[12:13]
	s_cbranch_vccnz .LBB0_58
	v_lshl_add_u64 v[22:23], v[52:53], 0, v[46:47]
	global_store_dwordx2 v[22:23], v[18:19], off offset:1536
